# v75 + MLA loops: first-half exps and packs spread evenly over the second score chain (2 exps + 1 pack per MFMA), own registers for exp results, PV hazard pad cut to the required distance
# baseline (speedup 1.0000x reference)
.LBB0_892:
	v_sub_co_u32_e64 v66, s[28:29], s4, 3
	s_and_b32 s21, s4, 1
	s_add_i32 s1, s4, 1
	v_readfirstlane_b32 s4, v66
	s_lshl_b64 s[36:37], s[4:5], 6
	s_and_b64 s[38:39], s[28:29], exec
	s_cselect_b32 s37, s15, s37
	s_cselect_b32 s36, s14, s36
	s_mul_i32 s39, s37, 0xc00
	s_mul_hi_u32 s40, s36, 0xc00
	s_cselect_b32 s4, s13, s23
	s_cselect_b32 s38, s12, s22
	s_add_i32 s40, s40, s39
	s_mul_i32 s39, s36, 0xc00
	s_add_u32 s38, s38, s39
	s_addc_u32 s39, s4, s40
	s_xor_b32 s4, s21, 1
	s_mulk_i32 s4, 0x6000
	s_add_i32 s4, s69, s4
	s_add_i32 m0, s4, 0x8000
	s_nop 0
	global_load_lds_dwordx4 v222, s[38:39]
	s_add_i32 m0, s4, 0xa000
	s_lshl_b64 s[36:37], s[36:37], 12
	global_load_lds_dwordx4 v223, s[38:39]
	s_add_i32 m0, s4, 0xc000
	s_and_b64 s[28:29], s[28:29], exec
	s_cselect_b32 s28, s24, s33
	s_cselect_b32 s4, s25, s35
	s_add_u32 s28, s28, s36
	s_addc_u32 s29, s4, s37
	s_lshl_b32 s4, s21, 14
	s_xor_b32 s36, s4, 0x4000
	s_add_i32 s36, s69, s36
	global_load_lds_dwordx4 v224, s[38:39]
	s_mov_b32 m0, s36
	s_mulk_i32 s21, 0x6000
	global_load_lds_dwordx4 v225, s[28:29]
	s_add_i32 m0, s36, 0x2000
	s_nop 0
	global_load_lds_dwordx4 v226, s[28:29]
	v_add_u32_e32 v70, s21, v179
	v_add_u32_e32 v71, v70, v178
	ds_read_b128 v[66:69], v71 offset:32768
	v_add_u32_e32 v153, v70, v180
	v_add_u32_e32 v155, v70, v181
	v_add_u32_e32 v157, v70, v182
	v_add_u32_e32 v159, v70, v183
	v_add_u32_e32 v193, v70, v184
	v_add_u32_e32 v198, v70, v185
	v_add_u32_e32 v199, v70, v186
	v_add_u32_e32 v200, v70, v187
	s_waitcnt lgkmcnt(0)
	v_mfma_f32_32x32x16_bf16 v[82:97], v[66:69], v[142:145], 0
	ds_read_b128 v[66:69], v153 offset:32768
	v_add_u32_e32 v201, v70, v188
	v_add_u32_e32 v202, v70, v189
	v_add_u32_e32 v203, v70, v190
	s_waitcnt lgkmcnt(0)
	v_mfma_f32_32x32x16_bf16 v[82:97], v[66:69], v[138:141], v[82:97]
	ds_read_b128 v[66:69], v155 offset:32768
	s_waitcnt lgkmcnt(0)
	v_mfma_f32_32x32x16_bf16 v[82:97], v[66:69], v[134:137], v[82:97]
	ds_read_b128 v[66:69], v157 offset:32768
	s_waitcnt lgkmcnt(0)
	v_mfma_f32_32x32x16_bf16 v[82:97], v[66:69], v[130:133], v[82:97]
	ds_read_b128 v[66:69], v159 offset:32768
	s_waitcnt lgkmcnt(0)
	v_mfma_f32_32x32x16_bf16 v[82:97], v[66:69], v[126:129], v[82:97]
	ds_read_b128 v[66:69], v193 offset:32768
	s_waitcnt lgkmcnt(0)
	v_mfma_f32_32x32x16_bf16 v[82:97], v[66:69], v[122:125], v[82:97]
	ds_read_b128 v[66:69], v198 offset:32768
	s_waitcnt lgkmcnt(0)
	v_mfma_f32_32x32x16_bf16 v[82:97], v[66:69], v[118:121], v[82:97]
	ds_read_b128 v[66:69], v199 offset:32768
	s_waitcnt lgkmcnt(0)
	v_mfma_f32_32x32x16_bf16 v[82:97], v[66:69], v[114:117], v[82:97]
	ds_read_b128 v[66:69], v200 offset:32768
	s_waitcnt lgkmcnt(0)
	v_mfma_f32_32x32x16_bf16 v[82:97], v[66:69], v[110:113], v[82:97]
	ds_read_b128 v[66:69], v201 offset:32768
	s_waitcnt lgkmcnt(0)
	v_mfma_f32_32x32x16_bf16 v[82:97], v[66:69], v[106:109], v[82:97]
	ds_read_b128 v[66:69], v202 offset:32768
	s_waitcnt lgkmcnt(0)
	v_mfma_f32_32x32x16_bf16 v[82:97], v[66:69], v[102:105], v[82:97]
	ds_read_b128 v[66:69], v203 offset:32768
	s_waitcnt lgkmcnt(0)
	v_mfma_f32_32x32x16_bf16 v[82:97], v[66:69], v[98:101], v[82:97]
	ds_read_b128 v[66:69], v71 offset:45056
	ds_read_b128 v[194:197], v153 offset:45056
	s_nop 9
	v_exp_f32_e32 v227, v82
	v_exp_f32_e32 v228, v83
	s_waitcnt lgkmcnt(0)
	v_mfma_f32_32x32x16_bf16 v[66:81], v[66:69], v[142:145], 0
	v_exp_f32_e32 v229, v84
	v_exp_f32_e32 v230, v85
	v_mfma_f32_32x32x16_bf16 v[66:81], v[194:197], v[138:141], v[66:81]
	ds_read_b128 v[194:197], v155 offset:45056
	v_exp_f32_e32 v231, v86
	v_exp_f32_e32 v232, v87
	v_cvt_pk_bf16_f32 v82, v227, v228
	v_add_u32_e32 v153, s4, v176
	s_waitcnt lgkmcnt(0)
	v_mfma_f32_32x32x16_bf16 v[66:81], v[194:197], v[134:137], v[66:81]
	ds_read_b128 v[194:197], v157 offset:45056
	v_exp_f32_e32 v204, v88
	v_exp_f32_e32 v205, v89
	v_cvt_pk_bf16_f32 v83, v229, v230
	s_waitcnt lgkmcnt(0)
	v_mfma_f32_32x32x16_bf16 v[66:81], v[194:197], v[130:133], v[66:81]
	ds_read_b128 v[194:197], v159 offset:45056
	v_exp_f32_e32 v206, v90
	v_exp_f32_e32 v207, v91
	v_cvt_pk_bf16_f32 v84, v231, v232
	s_waitcnt lgkmcnt(0)
	v_mfma_f32_32x32x16_bf16 v[66:81], v[194:197], v[126:129], v[66:81]
	ds_read_b128 v[194:197], v193 offset:45056
	v_exp_f32_e32 v208, v92
	v_exp_f32_e32 v209, v93
	v_cvt_pk_bf16_f32 v85, v204, v205
	s_waitcnt lgkmcnt(0)
	v_mfma_f32_32x32x16_bf16 v[66:81], v[194:197], v[122:125], v[66:81]
	ds_read_b128 v[194:197], v198 offset:45056
	v_exp_f32_e32 v210, v94
	v_exp_f32_e32 v211, v95
	v_cvt_pk_bf16_f32 v86, v206, v207
	s_waitcnt lgkmcnt(0)
	v_mfma_f32_32x32x16_bf16 v[66:81], v[194:197], v[118:121], v[66:81]
	ds_read_b128 v[194:197], v199 offset:45056
	v_exp_f32_e32 v212, v96
	v_exp_f32_e32 v213, v97
	v_cvt_pk_bf16_f32 v87, v208, v209
	s_waitcnt lgkmcnt(0)
	v_mfma_f32_32x32x16_bf16 v[66:81], v[194:197], v[114:117], v[66:81]
	ds_read_b128 v[194:197], v200 offset:45056
	v_cvt_pk_bf16_f32 v88, v210, v211
	s_waitcnt lgkmcnt(0)
	v_mfma_f32_32x32x16_bf16 v[66:81], v[194:197], v[110:113], v[66:81]
	ds_read_b128 v[194:197], v201 offset:45056
	v_cvt_pk_bf16_f32 v89, v212, v213
	s_waitcnt lgkmcnt(0)
	v_mfma_f32_32x32x16_bf16 v[66:81], v[194:197], v[106:109], v[66:81]
	ds_read_b128 v[194:197], v202 offset:45056
	s_waitcnt lgkmcnt(0)
	v_mfma_f32_32x32x16_bf16 v[66:81], v[194:197], v[102:105], v[66:81]
	ds_read_b128 v[194:197], v203 offset:45056
	s_waitcnt lgkmcnt(0)
	v_mfma_f32_32x32x16_bf16 v[66:81], v[194:197], v[98:101], v[66:81]
	ds_read_b64_tr_b16 v[90:91], v153 offset:0
	ds_read_b64_tr_b16 v[92:93], v153 offset:0x800
	ds_read_b64_tr_b16 v[94:95], v153 offset:0x1000
	ds_read_b64_tr_b16 v[96:97], v153 offset:0x1800
	ds_read_b64_tr_b16 v[194:195], v153 offset:0x200
	ds_read_b64_tr_b16 v[196:197], v153 offset:0xa00
	ds_read_b64_tr_b16 v[198:199], v153 offset:0x1200
	ds_read_b64_tr_b16 v[200:201], v153 offset:0x1a00
	s_waitcnt lgkmcnt(4)
	s_nop 0
	v_mfma_f32_32x32x16_bf16 v[2:17], v[82:85], v[90:93], v[2:17]
	s_nop 1
	v_exp_f32_e32 v214, v66
	v_exp_f32_e32 v215, v67
	v_exp_f32_e32 v216, v68
	v_exp_f32_e32 v217, v69
	v_mfma_f32_32x32x16_bf16 v[2:17], v[86:89], v[94:97], v[2:17]
	ds_read_b64_tr_b16 v[66:67], v153 offset:0x400
	ds_read_b64_tr_b16 v[68:69], v153 offset:0xc00
	ds_read_b64_tr_b16 v[90:91], v153 offset:0x1400
	ds_read_b64_tr_b16 v[92:93], v153 offset:0x1c00
	s_waitcnt lgkmcnt(4)
	v_mfma_f32_32x32x16_bf16 v[18:33], v[82:85], v[194:197], v[18:33]
	v_exp_f32_e32 v194, v70
	v_exp_f32_e32 v195, v71
	v_exp_f32_e32 v196, v72
	v_exp_f32_e32 v197, v73
	v_mfma_f32_32x32x16_bf16 v[18:33], v[86:89], v[198:201], v[18:33]
	ds_read_b64_tr_b16 v[70:71], v153 offset:0x600
	ds_read_b64_tr_b16 v[72:73], v153 offset:0xe00
	ds_read_b64_tr_b16 v[94:95], v153 offset:0x1600
	ds_read_b64_tr_b16 v[96:97], v153 offset:0x1e00
	s_waitcnt lgkmcnt(4)
	v_mfma_f32_32x32x16_bf16 v[34:49], v[82:85], v[66:69], v[34:49]
	v_exp_f32_e32 v198, v74
	v_exp_f32_e32 v199, v75
	v_exp_f32_e32 v200, v76
	v_exp_f32_e32 v201, v77
	v_mfma_f32_32x32x16_bf16 v[34:49], v[86:89], v[90:93], v[34:49]
	ds_read_b64_tr_b16 v[66:67], v153 offset:0x2000
	ds_read_b64_tr_b16 v[68:69], v153 offset:0x2800
	ds_read_b64_tr_b16 v[74:75], v153 offset:0x3000
	ds_read_b64_tr_b16 v[76:77], v153 offset:0x3800
	s_waitcnt lgkmcnt(4)
	v_mfma_f32_32x32x16_bf16 v[50:65], v[82:85], v[70:73], v[50:65]
	v_exp_f32_e32 v249, v78
	v_exp_f32_e32 v250, v79
	v_cvt_pk_bf16_f32 v72, v194, v195
	v_cvt_pk_bf16_f32 v73, v196, v197
	v_mfma_f32_32x32x16_bf16 v[50:65], v[86:89], v[94:97], v[50:65]
	v_exp_f32_e32 v251, v80
	v_exp_f32_e32 v248, v81
	v_cvt_pk_bf16_f32 v78, v198, v199
	v_cvt_pk_bf16_f32 v79, v200, v201
	v_cvt_pk_bf16_f32 v80, v249, v250
	v_cvt_pk_bf16_f32 v70, v214, v215
	v_cvt_pk_bf16_f32 v71, v216, v217
	v_cvt_pk_bf16_f32 v81, v251, v248
	ds_read_b64_tr_b16 v[82:83], v153 offset:0x2200
	ds_read_b64_tr_b16 v[84:85], v153 offset:0x2a00
	ds_read_b64_tr_b16 v[86:87], v153 offset:0x3200
	ds_read_b64_tr_b16 v[88:89], v153 offset:0x3a00
	s_waitcnt lgkmcnt(4)
	s_nop 0
	v_mfma_f32_32x32x16_bf16 v[2:17], v[70:73], v[66:69], v[2:17]
	v_add_f32_e32 v246, v227, v228
	v_add_f32_e32 v247, v214, v215
	v_add_f32_e32 v246, v246, v229
	v_add_f32_e32 v247, v247, v216
	v_mfma_f32_32x32x16_bf16 v[2:17], v[78:81], v[74:77], v[2:17]
	v_add_f32_e32 v246, v246, v230
	v_add_f32_e32 v247, v247, v217
	v_add_f32_e32 v246, v246, v231
	v_add_f32_e32 v247, v247, v194
	ds_read_b64_tr_b16 v[66:67], v153 offset:0x2400
	ds_read_b64_tr_b16 v[68:69], v153 offset:0x2c00
	ds_read_b64_tr_b16 v[74:75], v153 offset:0x3400
	ds_read_b64_tr_b16 v[76:77], v153 offset:0x3c00
	s_waitcnt lgkmcnt(4)
	v_mfma_f32_32x32x16_bf16 v[18:33], v[70:73], v[82:85], v[18:33]
	v_add_f32_e32 v246, v246, v232
	v_add_f32_e32 v247, v247, v195
	v_add_f32_e32 v246, v246, v204
	v_add_f32_e32 v247, v247, v196
	v_mfma_f32_32x32x16_bf16 v[18:33], v[78:81], v[86:89], v[18:33]
	v_add_f32_e32 v246, v246, v205
	v_add_f32_e32 v247, v247, v197
	v_add_f32_e32 v246, v246, v206
	v_add_f32_e32 v247, v247, v198
	ds_read_b64_tr_b16 v[82:83], v153 offset:0x2600
	ds_read_b64_tr_b16 v[84:85], v153 offset:0x2e00
	ds_read_b64_tr_b16 v[86:87], v153 offset:0x3600
	ds_read_b64_tr_b16 v[88:89], v153 offset:0x3e00
	s_waitcnt lgkmcnt(4)
	v_mfma_f32_32x32x16_bf16 v[34:49], v[70:73], v[66:69], v[34:49]
	v_add_f32_e32 v246, v246, v207
	v_add_f32_e32 v247, v247, v199
	v_add_f32_e32 v246, v246, v208
	v_add_f32_e32 v247, v247, v200
	v_mfma_f32_32x32x16_bf16 v[34:49], v[78:81], v[74:77], v[34:49]
	v_add_f32_e32 v246, v246, v209
	v_add_f32_e32 v247, v247, v201
	v_add_f32_e32 v246, v246, v210
	v_add_f32_e32 v247, v247, v249
	s_waitcnt lgkmcnt(0)
	v_mfma_f32_32x32x16_bf16 v[50:65], v[70:73], v[82:85], v[50:65]
	v_add_f32_e32 v246, v246, v211
	v_add_f32_e32 v247, v247, v250
	v_add_f32_e32 v246, v246, v212
	v_add_f32_e32 v247, v247, v251
	v_add_f32_e32 v246, v246, v213
	v_add_f32_e32 v247, v247, v248
	v_add_f32_e32 v246, v246, v247
	v_add_f32_e32 v151, v151, v246
	s_waitcnt vmcnt(0)
	s_add_u32 s14, s14, 64
	s_addc_u32 s15, s15, 0
	s_cmp_eq_u32 s0, s1
	s_mov_b32 s4, s1
	s_waitcnt vmcnt(0)
	s_barrier
	v_mfma_f32_32x32x16_bf16 v[50:65], v[78:81], v[86:89], v[50:65]
	s_cbranch_scc0 .LBB0_892
	s_lshl_b32 s1, s68, 2
	s_add_i32 s4, s1, 0
	s_and_b32 s0, s0, 1
	s_add_i32 s4, s4, 0x1e000
	s_mul_i32 s1, s0, 0x6000
	v_add_u32_e32 v70, s1, v179
	v_add_u32_e32 v71, v70, v178
	ds_read_b128 v[66:69], v71 offset:32768
	v_add_u32_e32 v153, v70, v180
	v_add_u32_e32 v155, v70, v181
	v_add_u32_e32 v157, v70, v182
	v_add_u32_e32 v159, v70, v183
	v_add_u32_e32 v160, v70, v184
	v_add_u32_e32 v161, v70, v185
	v_add_u32_e32 v162, v70, v186
	v_add_u32_e32 v163, v70, v187
	s_waitcnt lgkmcnt(0)
	v_mfma_f32_32x32x16_bf16 v[82:97], v[66:69], v[142:145], 0
	ds_read_b128 v[66:69], v153 offset:32768
	v_add_u32_e32 v170, v70, v188
	v_add_u32_e32 v171, v70, v189
	v_add_u32_e32 v172, v70, v190
	s_waitcnt lgkmcnt(0)
	v_mfma_f32_32x32x16_bf16 v[82:97], v[66:69], v[138:141], v[82:97]
	ds_read_b128 v[66:69], v155 offset:32768
	s_waitcnt lgkmcnt(0)
	v_mfma_f32_32x32x16_bf16 v[82:97], v[66:69], v[134:137], v[82:97]
	ds_read_b128 v[66:69], v157 offset:32768
	s_waitcnt lgkmcnt(0)
	v_mfma_f32_32x32x16_bf16 v[82:97], v[66:69], v[130:133], v[82:97]
	ds_read_b128 v[66:69], v159 offset:32768
	s_waitcnt lgkmcnt(0)
	v_mfma_f32_32x32x16_bf16 v[82:97], v[66:69], v[126:129], v[82:97]
	ds_read_b128 v[66:69], v160 offset:32768
	s_waitcnt lgkmcnt(0)
	v_mfma_f32_32x32x16_bf16 v[82:97], v[66:69], v[122:125], v[82:97]
	ds_read_b128 v[66:69], v161 offset:32768
	s_waitcnt lgkmcnt(0)
	v_mfma_f32_32x32x16_bf16 v[82:97], v[66:69], v[118:121], v[82:97]
	ds_read_b128 v[66:69], v162 offset:32768
	s_waitcnt lgkmcnt(0)
	v_mfma_f32_32x32x16_bf16 v[82:97], v[66:69], v[114:117], v[82:97]
	ds_read_b128 v[66:69], v163 offset:32768
	s_waitcnt lgkmcnt(0)
	v_mfma_f32_32x32x16_bf16 v[82:97], v[66:69], v[110:113], v[82:97]
	ds_read_b128 v[66:69], v170 offset:32768
	s_waitcnt lgkmcnt(0)
	v_mfma_f32_32x32x16_bf16 v[82:97], v[66:69], v[106:109], v[82:97]
	ds_read_b128 v[66:69], v171 offset:32768
	s_waitcnt lgkmcnt(0)
	v_mfma_f32_32x32x16_bf16 v[82:97], v[66:69], v[102:105], v[82:97]
	ds_read_b128 v[66:69], v172 offset:32768
	s_waitcnt lgkmcnt(0)
	v_mfma_f32_32x32x16_bf16 v[82:97], v[66:69], v[98:101], v[82:97]
	ds_read_b128 v[66:69], v71 offset:45056
	s_waitcnt lgkmcnt(0)
	v_mfma_f32_32x32x16_bf16 v[66:81], v[66:69], v[142:145], 0
	ds_read_b128 v[142:145], v153 offset:45056
	s_waitcnt lgkmcnt(0)
	v_mfma_f32_32x32x16_bf16 v[66:81], v[142:145], v[138:141], v[66:81]
	ds_read_b128 v[138:141], v155 offset:45056
	s_waitcnt lgkmcnt(0)
	v_mfma_f32_32x32x16_bf16 v[66:81], v[138:141], v[134:137], v[66:81]
	ds_read_b128 v[134:137], v157 offset:45056
	s_waitcnt lgkmcnt(0)
	v_mfma_f32_32x32x16_bf16 v[66:81], v[134:137], v[130:133], v[66:81]
	ds_read_b128 v[130:133], v159 offset:45056
	s_waitcnt lgkmcnt(0)
	v_mfma_f32_32x32x16_bf16 v[66:81], v[130:133], v[126:129], v[66:81]
	ds_read_b128 v[126:129], v160 offset:45056
	s_waitcnt lgkmcnt(0)
	v_mfma_f32_32x32x16_bf16 v[66:81], v[126:129], v[122:125], v[66:81]
	ds_read_b128 v[122:125], v161 offset:45056
	s_waitcnt lgkmcnt(0)
	v_mfma_f32_32x32x16_bf16 v[66:81], v[122:125], v[118:121], v[66:81]
	ds_read_b128 v[118:121], v162 offset:45056
	v_exp_f32_e32 v122, v97
	s_waitcnt lgkmcnt(0)
	v_mfma_f32_32x32x16_bf16 v[66:81], v[118:121], v[114:117], v[66:81]
	ds_read_b128 v[114:117], v163 offset:45056
	v_exp_f32_e32 v118, v93
	v_exp_f32_e32 v119, v94
	v_exp_f32_e32 v120, v95
	v_exp_f32_e32 v121, v96
	s_waitcnt lgkmcnt(0)
	v_mfma_f32_32x32x16_bf16 v[66:81], v[114:117], v[110:113], v[66:81]
	ds_read_b128 v[110:113], v170 offset:45056
	v_exp_f32_e32 v114, v89
	v_exp_f32_e32 v115, v90
	v_exp_f32_e32 v116, v91
	v_exp_f32_e32 v117, v92
	v_cvt_pk_bf16_f32 v89, v121, v122
	s_waitcnt lgkmcnt(0)
	v_mfma_f32_32x32x16_bf16 v[66:81], v[110:113], v[106:109], v[66:81]
	ds_read_b128 v[106:109], v171 offset:45056
	v_exp_f32_e32 v110, v85
	v_exp_f32_e32 v111, v86
	v_exp_f32_e32 v112, v87
	v_exp_f32_e32 v113, v88
	v_cvt_pk_bf16_f32 v86, v115, v116
	v_cvt_pk_bf16_f32 v87, v117, v118
	s_waitcnt lgkmcnt(0)
	v_mfma_f32_32x32x16_bf16 v[66:81], v[106:109], v[102:105], v[66:81]
	ds_read_b128 v[102:105], v172 offset:45056
	v_exp_f32_e32 v107, v82
	v_exp_f32_e32 v108, v83
	v_exp_f32_e32 v109, v84
	v_cvt_pk_bf16_f32 v84, v111, v112
	v_cvt_pk_bf16_f32 v85, v113, v114
	v_cvt_pk_bf16_f32 v82, v107, v108
	s_waitcnt lgkmcnt(0)
	v_mfma_f32_32x32x16_bf16 v[66:81], v[102:105], v[98:101], v[66:81]
	v_cvt_pk_bf16_f32 v83, v109, v110
	v_cvt_pk_bf16_f32 v88, v119, v120
	v_lshl_add_u32 v106, s0, 14, v176
	ds_read_b64_tr_b16 v[90:91], v106 offset:0
	ds_read_b64_tr_b16 v[92:93], v106 offset:0x800
	ds_read_b64_tr_b16 v[94:95], v106 offset:0x1000
	ds_read_b64_tr_b16 v[96:97], v106 offset:0x1800
	ds_read_b64_tr_b16 v[98:99], v106 offset:0x200
	ds_read_b64_tr_b16 v[100:101], v106 offset:0xa00
	ds_read_b64_tr_b16 v[102:103], v106 offset:0x1200
	ds_read_b64_tr_b16 v[104:105], v106 offset:0x1a00
	s_waitcnt lgkmcnt(4)
	s_nop 0
	v_mfma_f32_32x32x16_bf16 v[2:17], v[82:85], v[90:93], v[2:17]
	s_nop 2
	v_exp_f32_e32 v123, v66
	v_exp_f32_e32 v124, v67
	v_exp_f32_e32 v125, v68
	v_exp_f32_e32 v126, v69
	v_mfma_f32_32x32x16_bf16 v[2:17], v[86:89], v[94:97], v[2:17]
	ds_read_b64_tr_b16 v[66:67], v106 offset:0x400
	ds_read_b64_tr_b16 v[68:69], v106 offset:0xc00
	ds_read_b64_tr_b16 v[90:91], v106 offset:0x1400
	ds_read_b64_tr_b16 v[92:93], v106 offset:0x1c00
	s_waitcnt lgkmcnt(4)
	v_mfma_f32_32x32x16_bf16 v[18:33], v[82:85], v[98:101], v[18:33]
	v_exp_f32_e32 v98, v70
	v_exp_f32_e32 v99, v71
	v_exp_f32_e32 v100, v72
	v_exp_f32_e32 v101, v73
	v_mfma_f32_32x32x16_bf16 v[18:33], v[86:89], v[102:105], v[18:33]
	ds_read_b64_tr_b16 v[70:71], v106 offset:0x600
	ds_read_b64_tr_b16 v[72:73], v106 offset:0xe00
	ds_read_b64_tr_b16 v[94:95], v106 offset:0x1600
	ds_read_b64_tr_b16 v[96:97], v106 offset:0x1e00
	s_waitcnt lgkmcnt(4)
	v_mfma_f32_32x32x16_bf16 v[34:49], v[82:85], v[66:69], v[34:49]
	v_exp_f32_e32 v102, v74
	v_exp_f32_e32 v103, v75
	v_exp_f32_e32 v104, v76
	v_exp_f32_e32 v105, v77
	v_mfma_f32_32x32x16_bf16 v[34:49], v[86:89], v[90:93], v[34:49]
	ds_read_b64_tr_b16 v[74:75], v106 offset:0x2000
	ds_read_b64_tr_b16 v[76:77], v106 offset:0x2800
	ds_read_b64_tr_b16 v[90:91], v106 offset:0x3000
	ds_read_b64_tr_b16 v[92:93], v106 offset:0x3800
	s_waitcnt lgkmcnt(4)
	v_add_f32_e32 v66, v107, v108
	v_add_f32_e32 v67, v123, v124
	v_mfma_f32_32x32x16_bf16 v[50:65], v[82:85], v[70:73], v[50:65]
	v_add_f32_e32 v66, v66, v109
	v_add_f32_e32 v67, v67, v125
	v_exp_f32_e32 v127, v78
	v_add_f32_e32 v66, v66, v110
	v_add_f32_e32 v67, v67, v126
	v_exp_f32_e32 v128, v79
	v_add_f32_e32 v66, v66, v111
	v_add_f32_e32 v67, v67, v98
	v_mfma_f32_32x32x16_bf16 v[50:65], v[86:89], v[94:97], v[50:65]
	v_add_f32_e32 v66, v66, v112
	v_add_f32_e32 v67, v67, v99
	v_exp_f32_e32 v129, v80
	v_add_f32_e32 v66, v66, v113
	v_add_f32_e32 v67, v67, v100
	v_exp_f32_e32 v81, v81
	v_add_f32_e32 v66, v66, v114
	v_add_f32_e32 v67, v67, v101
	v_cvt_pk_bf16_f32 v68, v123, v124
	v_add_f32_e32 v66, v66, v115
	v_add_f32_e32 v67, v67, v102
	v_cvt_pk_bf16_f32 v69, v125, v126
	v_add_f32_e32 v66, v66, v116
	v_add_f32_e32 v67, v67, v103
	v_cvt_pk_bf16_f32 v70, v98, v99
	v_add_f32_e32 v66, v66, v117
	v_add_f32_e32 v67, v67, v104
	v_cvt_pk_bf16_f32 v71, v100, v101
	v_add_f32_e32 v66, v66, v118
	v_add_f32_e32 v67, v67, v105
	v_cvt_pk_bf16_f32 v78, v102, v103
	v_add_f32_e32 v66, v66, v119
	v_add_f32_e32 v67, v67, v127
	v_cvt_pk_bf16_f32 v79, v104, v105
	v_add_f32_e32 v66, v66, v120
	v_add_f32_e32 v67, v67, v128
	v_cvt_pk_bf16_f32 v80, v127, v128
	v_add_f32_e32 v66, v66, v121
	v_add_f32_e32 v67, v67, v129
	v_add_f32_e32 v66, v66, v122
	v_add_f32_e32 v67, v67, v81
	v_cvt_pk_bf16_f32 v81, v129, v81
	v_add_f32_e32 v66, v66, v67
	v_add_f32_e32 v66, v151, v66
	v_mov_b32_e32 v67, v66
	s_nop 1
	v_permlane32_swap_b32_e32 v66, v67
	ds_read_b64_tr_b16 v[82:83], v106 offset:0x2200
	ds_read_b64_tr_b16 v[84:85], v106 offset:0x2a00
	ds_read_b64_tr_b16 v[86:87], v106 offset:0x3200
	ds_read_b64_tr_b16 v[88:89], v106 offset:0x3a00
	s_waitcnt lgkmcnt(4)
	v_mfma_f32_32x32x16_bf16 v[2:17], v[68:71], v[74:77], v[2:17]
	s_nop 0
	v_mfma_f32_32x32x16_bf16 v[2:17], v[78:81], v[90:93], v[2:17]
	ds_read_b64_tr_b16 v[72:73], v106 offset:0x2400
	ds_read_b64_tr_b16 v[74:75], v106 offset:0x2c00
	ds_read_b64_tr_b16 v[90:91], v106 offset:0x3400
	ds_read_b64_tr_b16 v[92:93], v106 offset:0x3c00
	s_waitcnt lgkmcnt(4)
	v_mfma_f32_32x32x16_bf16 v[18:33], v[68:71], v[82:85], v[18:33]
	v_mfma_f32_32x32x16_bf16 v[18:33], v[78:81], v[86:89], v[18:33]
	ds_read_b64_tr_b16 v[82:83], v106 offset:0x2600
	ds_read_b64_tr_b16 v[84:85], v106 offset:0x2e00
	ds_read_b64_tr_b16 v[86:87], v106 offset:0x3600
	ds_read_b64_tr_b16 v[88:89], v106 offset:0x3e00
	s_waitcnt lgkmcnt(4)
	v_mfma_f32_32x32x16_bf16 v[34:49], v[68:71], v[72:75], v[34:49]
	v_mfma_f32_32x32x16_bf16 v[34:49], v[78:81], v[90:93], v[34:49]
	s_waitcnt lgkmcnt(0)
	v_mfma_f32_32x32x16_bf16 v[50:65], v[68:71], v[82:85], v[50:65]
	s_waitcnt vmcnt(0)
	s_barrier
	v_mfma_f32_32x32x16_bf16 v[50:65], v[78:81], v[86:89], v[50:65]
	s_and_saveexec_b64 s[0:1], s[2:3]
	s_cbranch_execz .LBB0_886
	v_add_f32_e32 v66, v66, v67
	v_lshl_add_u32 v68, v1, 2, s4
	ds_write_b32 v68, v66
	s_branch .LBB0_886

.LBB0_2312:
	v_add_co_u32_e64 v66, s[14:15], s4, 3
	s_nop 0
	v_readfirstlane_b32 s21, v66
	s_and_b32 s21, s21, 1
	s_lshl_b64 s[28:29], s[4:5], 6
	s_and_b64 s[40:41], s[14:15], exec
	s_cselect_b32 s29, s1, s29
	s_cselect_b32 s28, s0, s28
	s_mul_i32 s42, s29, 0xc00
	s_mul_hi_u32 s43, s28, 0xc00
	s_cselect_b32 s41, s13, s39
	s_cselect_b32 s40, s12, s38
	s_add_i32 s43, s43, s42
	s_mul_i32 s42, s28, 0xc00
	s_add_u32 s40, s40, s42
	s_addc_u32 s41, s41, s43
	s_xor_b32 s42, s21, 1
	s_mulk_i32 s42, 0x6000
	s_add_i32 s42, s53, s42
	s_add_i32 m0, s42, 0x8000
	s_nop 0
	global_load_lds_dwordx4 v238, s[40:41]
	s_add_i32 m0, s42, 0xa000
	s_lshl_b64 s[28:29], s[28:29], 12
	global_load_lds_dwordx4 v239, s[40:41]
	s_add_i32 m0, s42, 0xc000
	s_and_b64 s[14:15], s[14:15], exec
	s_cselect_b32 s14, s44, s46
	s_cselect_b32 s15, s45, s47
	s_add_u32 s14, s14, s28
	s_addc_u32 s15, s15, s29
	s_lshl_b32 s28, s21, 14
	s_xor_b32 s29, s28, 0x4000
	s_add_i32 s29, s53, s29
	global_load_lds_dwordx4 v240, s[40:41]
	s_mov_b32 m0, s29
	s_mulk_i32 s21, 0x6000
	global_load_lds_dwordx4 v241, s[14:15]
	s_add_i32 m0, s29, 0x2000
	s_nop 0
	global_load_lds_dwordx4 v244, s[14:15]
	v_add_u32_e32 v74, s21, v182
	v_add_u32_e32 v75, v74, v181
	ds_read_b128 v[66:69], v75 offset:32768
	v_add_u32_e32 v76, v74, v183
	ds_read_b128 v[70:73], v76 offset:32768
	v_add_u32_e32 v153, v74, v184
	v_add_u32_e32 v155, v74, v185
	v_add_u32_e32 v157, v74, v186
	v_add_u32_e32 v159, v74, v187
	v_add_u32_e32 v209, v74, v188
	v_add_u32_e32 v218, v74, v189
	s_waitcnt lgkmcnt(0)
	v_mfma_f32_32x32x16_bf16 v[82:97], v[66:69], v[142:145], 0
	ds_read_b128 v[66:69], v153 offset:32768
	v_add_u32_e32 v219, v74, v190
	v_add_u32_e32 v220, v74, v191
	v_add_u32_e32 v221, v74, v192
	v_add_u32_e32 v222, v74, v193
	v_mfma_f32_32x32x16_bf16 v[82:97], v[70:73], v[138:141], v[82:97]
	ds_read_b128 v[70:73], v155 offset:32768
	s_waitcnt lgkmcnt(0)
	v_mfma_f32_32x32x16_bf16 v[82:97], v[66:69], v[134:137], v[82:97]
	ds_read_b128 v[66:69], v157 offset:32768
	v_mfma_f32_32x32x16_bf16 v[82:97], v[70:73], v[130:133], v[82:97]
	ds_read_b128 v[70:73], v159 offset:32768
	s_waitcnt lgkmcnt(0)
	v_mfma_f32_32x32x16_bf16 v[82:97], v[66:69], v[126:129], v[82:97]
	ds_read_b128 v[66:69], v209 offset:32768
	v_mfma_f32_32x32x16_bf16 v[82:97], v[70:73], v[122:125], v[82:97]
	ds_read_b128 v[70:73], v218 offset:32768
	s_waitcnt lgkmcnt(0)
	v_mfma_f32_32x32x16_bf16 v[82:97], v[66:69], v[118:121], v[82:97]
	ds_read_b128 v[66:69], v219 offset:32768
	v_mfma_f32_32x32x16_bf16 v[82:97], v[70:73], v[114:117], v[82:97]
	ds_read_b128 v[70:73], v220 offset:32768
	s_waitcnt lgkmcnt(0)
	v_mfma_f32_32x32x16_bf16 v[82:97], v[66:69], v[110:113], v[82:97]
	ds_read_b128 v[66:69], v221 offset:32768
	v_mfma_f32_32x32x16_bf16 v[82:97], v[70:73], v[106:109], v[82:97]
	ds_read_b128 v[70:73], v222 offset:32768
	s_waitcnt lgkmcnt(0)
	v_mfma_f32_32x32x16_bf16 v[82:97], v[66:69], v[102:105], v[82:97]
	v_mfma_f32_32x32x16_bf16 v[82:97], v[70:73], v[98:101], v[82:97]
	ds_read_b128 v[66:69], v75 offset:45056
	ds_read_b128 v[210:213], v76 offset:45056
	s_nop 9
	v_exp_f32_e32 v245, v82
	v_exp_f32_e32 v252, v83
	s_waitcnt lgkmcnt(0)
	v_mfma_f32_32x32x16_bf16 v[66:81], v[66:69], v[142:145], 0
	v_exp_f32_e32 v253, v84
	v_exp_f32_e32 v254, v85
	v_mfma_f32_32x32x16_bf16 v[66:81], v[210:213], v[138:141], v[66:81]
	ds_read_b128 v[210:213], v153 offset:45056
	ds_read_b128 v[214:217], v155 offset:45056
	v_exp_f32_e32 v226, v86
	v_exp_f32_e32 v227, v87
	v_cvt_pk_bf16_f32 v82, v245, v252
	s_waitcnt lgkmcnt(0)
	v_mfma_f32_32x32x16_bf16 v[66:81], v[210:213], v[134:137], v[66:81]
	v_exp_f32_e32 v228, v88
	v_exp_f32_e32 v229, v89
	v_cvt_pk_bf16_f32 v83, v253, v254
	v_mfma_f32_32x32x16_bf16 v[66:81], v[214:217], v[130:133], v[66:81]
	ds_read_b128 v[210:213], v157 offset:45056
	ds_read_b128 v[214:217], v159 offset:45056
	v_exp_f32_e32 v230, v90
	v_exp_f32_e32 v231, v91
	v_cvt_pk_bf16_f32 v84, v226, v227
	v_add_u32_e32 v153, s28, v179
	s_waitcnt lgkmcnt(0)
	v_mfma_f32_32x32x16_bf16 v[66:81], v[210:213], v[126:129], v[66:81]
	v_exp_f32_e32 v232, v92
	v_exp_f32_e32 v233, v93
	v_cvt_pk_bf16_f32 v85, v228, v229
	v_mfma_f32_32x32x16_bf16 v[66:81], v[214:217], v[122:125], v[66:81]
	ds_read_b128 v[210:213], v209 offset:45056
	ds_read_b128 v[214:217], v218 offset:45056
	v_exp_f32_e32 v234, v94
	v_exp_f32_e32 v235, v95
	v_cvt_pk_bf16_f32 v86, v230, v231
	s_waitcnt lgkmcnt(0)
	v_mfma_f32_32x32x16_bf16 v[66:81], v[210:213], v[118:121], v[66:81]
	ds_read_b128 v[210:213], v219 offset:45056
	v_exp_f32_e32 v236, v96
	v_exp_f32_e32 v237, v97
	v_cvt_pk_bf16_f32 v87, v232, v233
	v_mfma_f32_32x32x16_bf16 v[66:81], v[214:217], v[114:117], v[66:81]
	ds_read_b128 v[214:217], v220 offset:45056
	ds_read_b128 v[218:221], v221 offset:45056
	ds_read_b128 v[222:225], v222 offset:45056
	v_cvt_pk_bf16_f32 v88, v234, v235
	s_waitcnt lgkmcnt(0)
	v_mfma_f32_32x32x16_bf16 v[66:81], v[210:213], v[110:113], v[66:81]
	v_cvt_pk_bf16_f32 v89, v236, v237
	v_mfma_f32_32x32x16_bf16 v[66:81], v[214:217], v[106:109], v[66:81]
	v_mfma_f32_32x32x16_bf16 v[66:81], v[218:221], v[102:105], v[66:81]
	v_mfma_f32_32x32x16_bf16 v[66:81], v[222:225], v[98:101], v[66:81]
	ds_read_b64_tr_b16 v[90:91], v153 offset:0
	ds_read_b64_tr_b16 v[92:93], v153 offset:0x800
	ds_read_b64_tr_b16 v[94:95], v153 offset:0x1000
	ds_read_b64_tr_b16 v[96:97], v153 offset:0x1800
	ds_read_b64_tr_b16 v[210:211], v153 offset:0x200
	ds_read_b64_tr_b16 v[212:213], v153 offset:0xa00
	ds_read_b64_tr_b16 v[214:215], v153 offset:0x1200
	ds_read_b64_tr_b16 v[216:217], v153 offset:0x1a00
	s_waitcnt lgkmcnt(4)
	s_nop 0
	v_mfma_f32_32x32x16_bf16 v[2:17], v[82:85], v[90:93], v[2:17]
	s_nop 1
	v_exp_f32_e32 v218, v66
	v_exp_f32_e32 v219, v67
	v_exp_f32_e32 v220, v68
	v_exp_f32_e32 v221, v69
	v_mfma_f32_32x32x16_bf16 v[2:17], v[86:89], v[94:97], v[2:17]
	ds_read_b64_tr_b16 v[66:67], v153 offset:0x400
	ds_read_b64_tr_b16 v[68:69], v153 offset:0xc00
	ds_read_b64_tr_b16 v[90:91], v153 offset:0x1400
	ds_read_b64_tr_b16 v[92:93], v153 offset:0x1c00
	s_waitcnt lgkmcnt(4)
	v_mfma_f32_32x32x16_bf16 v[18:33], v[82:85], v[210:213], v[18:33]
	v_exp_f32_e32 v210, v70
	v_exp_f32_e32 v211, v71
	v_exp_f32_e32 v212, v72
	v_exp_f32_e32 v213, v73
	v_mfma_f32_32x32x16_bf16 v[18:33], v[86:89], v[214:217], v[18:33]
	ds_read_b64_tr_b16 v[70:71], v153 offset:0x600
	ds_read_b64_tr_b16 v[72:73], v153 offset:0xe00
	ds_read_b64_tr_b16 v[94:95], v153 offset:0x1600
	ds_read_b64_tr_b16 v[96:97], v153 offset:0x1e00
	s_waitcnt lgkmcnt(4)
	v_mfma_f32_32x32x16_bf16 v[34:49], v[82:85], v[66:69], v[34:49]
	v_exp_f32_e32 v214, v74
	v_exp_f32_e32 v215, v75
	v_exp_f32_e32 v216, v76
	v_exp_f32_e32 v217, v77
	v_mfma_f32_32x32x16_bf16 v[34:49], v[86:89], v[90:93], v[34:49]
	ds_read_b64_tr_b16 v[66:67], v153 offset:0x2000
	ds_read_b64_tr_b16 v[68:69], v153 offset:0x2800
	ds_read_b64_tr_b16 v[74:75], v153 offset:0x3000
	ds_read_b64_tr_b16 v[76:77], v153 offset:0x3800
	s_waitcnt lgkmcnt(4)
	v_exp_f32_e32 v90, v78
	v_mfma_f32_32x32x16_bf16 v[50:65], v[82:85], v[70:73], v[50:65]
	v_exp_f32_e32 v91, v79
	v_cvt_pk_bf16_f32 v72, v210, v211
	v_cvt_pk_bf16_f32 v73, v212, v213
	v_mfma_f32_32x32x16_bf16 v[50:65], v[86:89], v[94:97], v[50:65]
	v_exp_f32_e32 v92, v80
	v_exp_f32_e32 v248, v81
	v_cvt_pk_bf16_f32 v78, v214, v215
	v_cvt_pk_bf16_f32 v79, v216, v217
	v_cvt_pk_bf16_f32 v80, v90, v91
	v_cvt_pk_bf16_f32 v70, v218, v219
	v_cvt_pk_bf16_f32 v71, v220, v221
	v_cvt_pk_bf16_f32 v81, v92, v248
	ds_read_b64_tr_b16 v[82:83], v153 offset:0x2200
	ds_read_b64_tr_b16 v[84:85], v153 offset:0x2a00
	ds_read_b64_tr_b16 v[86:87], v153 offset:0x3200
	ds_read_b64_tr_b16 v[88:89], v153 offset:0x3a00
	s_waitcnt lgkmcnt(4)
	s_nop 0
	v_mfma_f32_32x32x16_bf16 v[2:17], v[70:73], v[66:69], v[2:17]
	v_add_f32_e32 v246, v245, v252
	v_add_f32_e32 v247, v218, v219
	v_add_f32_e32 v246, v246, v253
	v_add_f32_e32 v247, v247, v220
	v_mfma_f32_32x32x16_bf16 v[2:17], v[78:81], v[74:77], v[2:17]
	v_add_f32_e32 v246, v246, v254
	v_add_f32_e32 v247, v247, v221
	v_add_f32_e32 v246, v246, v226
	v_add_f32_e32 v247, v247, v210
	ds_read_b64_tr_b16 v[66:67], v153 offset:0x2400
	ds_read_b64_tr_b16 v[68:69], v153 offset:0x2c00
	ds_read_b64_tr_b16 v[74:75], v153 offset:0x3400
	ds_read_b64_tr_b16 v[76:77], v153 offset:0x3c00
	s_waitcnt lgkmcnt(4)
	v_mfma_f32_32x32x16_bf16 v[18:33], v[70:73], v[82:85], v[18:33]
	v_add_f32_e32 v246, v246, v227
	v_add_f32_e32 v247, v247, v211
	v_add_f32_e32 v246, v246, v228
	v_add_f32_e32 v247, v247, v212
	v_mfma_f32_32x32x16_bf16 v[18:33], v[78:81], v[86:89], v[18:33]
	v_add_f32_e32 v246, v246, v229
	v_add_f32_e32 v247, v247, v213
	v_add_f32_e32 v246, v246, v230
	v_add_f32_e32 v247, v247, v214
	ds_read_b64_tr_b16 v[82:83], v153 offset:0x2600
	ds_read_b64_tr_b16 v[84:85], v153 offset:0x2e00
	ds_read_b64_tr_b16 v[86:87], v153 offset:0x3600
	ds_read_b64_tr_b16 v[88:89], v153 offset:0x3e00
	s_waitcnt lgkmcnt(4)
	v_mfma_f32_32x32x16_bf16 v[34:49], v[70:73], v[66:69], v[34:49]
	v_add_f32_e32 v246, v246, v231
	v_add_f32_e32 v247, v247, v215
	v_add_f32_e32 v246, v246, v232
	v_add_f32_e32 v247, v247, v216
	v_mfma_f32_32x32x16_bf16 v[34:49], v[78:81], v[74:77], v[34:49]
	v_add_f32_e32 v246, v246, v233
	v_add_f32_e32 v247, v247, v217
	v_add_f32_e32 v246, v246, v234
	v_add_f32_e32 v247, v247, v90
	s_waitcnt lgkmcnt(0)
	v_mfma_f32_32x32x16_bf16 v[50:65], v[70:73], v[82:85], v[50:65]
	v_add_f32_e32 v246, v246, v235
	v_add_f32_e32 v247, v247, v91
	v_add_f32_e32 v246, v246, v236
	v_add_f32_e32 v247, v247, v92
	v_add_f32_e32 v246, v246, v237
	v_add_f32_e32 v247, v247, v248
	v_add_f32_e32 v246, v246, v247
	v_add_f32_e32 v151, v151, v246
	s_waitcnt vmcnt(0)
	s_add_u32 s0, s0, 64
	s_addc_u32 s1, s1, 0
	s_add_i32 s4, s4, 1
	s_cmpk_eq_i32 s0, 0x4100
	s_waitcnt vmcnt(0)
	s_barrier
	v_mfma_f32_32x32x16_bf16 v[50:65], v[78:81], v[86:89], v[50:65]
	s_cbranch_scc0 .LBB0_2312
	s_lshl_b32 s0, s52, 2
	s_add_i32 s4, s0, 0
	s_add_i32 s4, s4, 0x1e000
	ds_read_b128 v[66:69], v196
	ds_read_b128 v[70:73], v197
	s_waitcnt lgkmcnt(1)
	v_mfma_f32_32x32x16_bf16 v[82:97], v[66:69], v[142:145], 0
	s_waitcnt lgkmcnt(0)
	v_mfma_f32_32x32x16_bf16 v[82:97], v[70:73], v[138:141], v[82:97]
	ds_read_b128 v[66:69], v198
	ds_read_b128 v[70:73], v199
	s_waitcnt lgkmcnt(1)
	v_mfma_f32_32x32x16_bf16 v[82:97], v[66:69], v[134:137], v[82:97]
	s_waitcnt lgkmcnt(0)
	v_mfma_f32_32x32x16_bf16 v[82:97], v[70:73], v[130:133], v[82:97]
	ds_read_b128 v[66:69], v200
	ds_read_b128 v[70:73], v201
	s_waitcnt lgkmcnt(1)
	v_mfma_f32_32x32x16_bf16 v[82:97], v[66:69], v[126:129], v[82:97]
	s_waitcnt lgkmcnt(0)
	v_mfma_f32_32x32x16_bf16 v[82:97], v[70:73], v[122:125], v[82:97]
	ds_read_b128 v[66:69], v202
	ds_read_b128 v[70:73], v203
	s_waitcnt lgkmcnt(1)
	v_mfma_f32_32x32x16_bf16 v[82:97], v[66:69], v[118:121], v[82:97]
	s_waitcnt lgkmcnt(0)
	v_mfma_f32_32x32x16_bf16 v[82:97], v[70:73], v[114:117], v[82:97]
	ds_read_b128 v[66:69], v204
	ds_read_b128 v[70:73], v205
	s_waitcnt lgkmcnt(1)
	v_mfma_f32_32x32x16_bf16 v[82:97], v[66:69], v[110:113], v[82:97]
	s_waitcnt lgkmcnt(0)
	v_mfma_f32_32x32x16_bf16 v[82:97], v[70:73], v[106:109], v[82:97]
	ds_read_b128 v[66:69], v206
	ds_read_b128 v[70:73], v207
	s_waitcnt lgkmcnt(1)
	v_mfma_f32_32x32x16_bf16 v[82:97], v[66:69], v[102:105], v[82:97]
	s_waitcnt lgkmcnt(0)
	v_mfma_f32_32x32x16_bf16 v[82:97], v[70:73], v[98:101], v[82:97]
	ds_read_b128 v[66:69], v196 offset:12288
	ds_read_b128 v[160:163], v197 offset:12288
	s_waitcnt lgkmcnt(1)
	v_mfma_f32_32x32x16_bf16 v[66:81], v[66:69], v[142:145], 0
	s_waitcnt lgkmcnt(0)
	v_mfma_f32_32x32x16_bf16 v[66:81], v[160:163], v[138:141], v[66:81]
	ds_read_b128 v[138:141], v198 offset:12288
	ds_read_b128 v[142:145], v199 offset:12288
	s_waitcnt lgkmcnt(1)
	v_mfma_f32_32x32x16_bf16 v[66:81], v[138:141], v[134:137], v[66:81]
	s_waitcnt lgkmcnt(0)
	v_mfma_f32_32x32x16_bf16 v[66:81], v[142:145], v[130:133], v[66:81]
	ds_read_b128 v[130:133], v200 offset:12288
	ds_read_b128 v[134:137], v201 offset:12288
	s_waitcnt lgkmcnt(1)
	v_mfma_f32_32x32x16_bf16 v[66:81], v[130:133], v[126:129], v[66:81]
	v_exp_f32_e32 v130, v82
	v_exp_f32_e32 v131, v83
	v_exp_f32_e32 v132, v84
	v_cvt_pk_bf16_f32 v82, v130, v131
	s_waitcnt lgkmcnt(0)
	v_mfma_f32_32x32x16_bf16 v[66:81], v[134:137], v[122:125], v[66:81]
	ds_read_b128 v[122:125], v202 offset:12288
	ds_read_b128 v[126:129], v203 offset:12288
	s_waitcnt lgkmcnt(1)
	v_mfma_f32_32x32x16_bf16 v[66:81], v[122:125], v[118:121], v[66:81]
	s_waitcnt lgkmcnt(0)
	v_mfma_f32_32x32x16_bf16 v[66:81], v[126:129], v[114:117], v[66:81]
	ds_read_b128 v[114:117], v204 offset:12288
	ds_read_b128 v[118:121], v205 offset:12288
	ds_read_b128 v[122:125], v206 offset:12288
	ds_read_b128 v[126:129], v207 offset:12288
	s_waitcnt lgkmcnt(3)
	v_mfma_f32_32x32x16_bf16 v[66:81], v[114:117], v[110:113], v[66:81]
	v_exp_f32_e32 v110, v85
	v_exp_f32_e32 v111, v86
	v_exp_f32_e32 v112, v87
	v_exp_f32_e32 v113, v88
	v_exp_f32_e32 v114, v89
	v_exp_f32_e32 v115, v90
	v_exp_f32_e32 v116, v91
	s_waitcnt lgkmcnt(2)
	v_mfma_f32_32x32x16_bf16 v[66:81], v[118:121], v[106:109], v[66:81]
	v_exp_f32_e32 v106, v92
	v_exp_f32_e32 v107, v93
	v_exp_f32_e32 v108, v94
	v_exp_f32_e32 v109, v95
	v_exp_f32_e32 v117, v96
	v_exp_f32_e32 v118, v97
	v_cvt_pk_bf16_f32 v83, v132, v110
	s_waitcnt lgkmcnt(1)
	v_mfma_f32_32x32x16_bf16 v[66:81], v[122:125], v[102:105], v[66:81]
	v_cvt_pk_bf16_f32 v84, v111, v112
	v_cvt_pk_bf16_f32 v85, v113, v114
	v_cvt_pk_bf16_f32 v86, v115, v116
	v_cvt_pk_bf16_f32 v87, v106, v107
	v_cvt_pk_bf16_f32 v88, v108, v109
	v_cvt_pk_bf16_f32 v89, v117, v118
	s_waitcnt lgkmcnt(0)
	v_mfma_f32_32x32x16_bf16 v[66:81], v[126:129], v[98:101], v[66:81]
	ds_read_b64_tr_b16 v[90:91], v208 offset:0
	ds_read_b64_tr_b16 v[92:93], v208 offset:0x800
	ds_read_b64_tr_b16 v[94:95], v208 offset:0x1000
	ds_read_b64_tr_b16 v[96:97], v208 offset:0x1800
	ds_read_b64_tr_b16 v[98:99], v208 offset:0x200
	ds_read_b64_tr_b16 v[100:101], v208 offset:0xa00
	ds_read_b64_tr_b16 v[102:103], v208 offset:0x1200
	ds_read_b64_tr_b16 v[104:105], v208 offset:0x1a00
	s_waitcnt lgkmcnt(4)
	s_nop 0
	v_mfma_f32_32x32x16_bf16 v[2:17], v[82:85], v[90:93], v[2:17]
	s_nop 6
	v_exp_f32_e32 v119, v66
	v_exp_f32_e32 v120, v67
	v_exp_f32_e32 v121, v68
	v_exp_f32_e32 v122, v69
	v_mfma_f32_32x32x16_bf16 v[2:17], v[86:89], v[94:97], v[2:17]
	ds_read_b64_tr_b16 v[66:67], v208 offset:0x400
	ds_read_b64_tr_b16 v[68:69], v208 offset:0xc00
	ds_read_b64_tr_b16 v[90:91], v208 offset:0x1400
	ds_read_b64_tr_b16 v[92:93], v208 offset:0x1c00
	s_waitcnt lgkmcnt(4)
	v_mfma_f32_32x32x16_bf16 v[18:33], v[82:85], v[98:101], v[18:33]
	v_exp_f32_e32 v98, v70
	v_exp_f32_e32 v99, v71
	v_exp_f32_e32 v100, v72
	v_exp_f32_e32 v101, v73
	v_mfma_f32_32x32x16_bf16 v[18:33], v[86:89], v[102:105], v[18:33]
	ds_read_b64_tr_b16 v[70:71], v208 offset:0x600
	ds_read_b64_tr_b16 v[72:73], v208 offset:0xe00
	ds_read_b64_tr_b16 v[94:95], v208 offset:0x1600
	ds_read_b64_tr_b16 v[96:97], v208 offset:0x1e00
	s_waitcnt lgkmcnt(4)
	v_mfma_f32_32x32x16_bf16 v[34:49], v[82:85], v[66:69], v[34:49]
	v_exp_f32_e32 v102, v74
	v_exp_f32_e32 v103, v75
	v_exp_f32_e32 v104, v76
	v_exp_f32_e32 v105, v77
	v_mfma_f32_32x32x16_bf16 v[34:49], v[86:89], v[90:93], v[34:49]
	ds_read_b64_tr_b16 v[74:75], v208 offset:0x2000
	ds_read_b64_tr_b16 v[76:77], v208 offset:0x2800
	ds_read_b64_tr_b16 v[90:91], v208 offset:0x3000
	ds_read_b64_tr_b16 v[92:93], v208 offset:0x3800
	s_waitcnt lgkmcnt(4)
	v_add_f32_e32 v66, v130, v131
	v_add_f32_e32 v67, v119, v120
	v_mfma_f32_32x32x16_bf16 v[50:65], v[82:85], v[70:73], v[50:65]
	v_add_f32_e32 v66, v66, v132
	v_add_f32_e32 v67, v67, v121
	v_exp_f32_e32 v123, v78
	v_add_f32_e32 v66, v66, v110
	v_add_f32_e32 v67, v67, v122
	v_exp_f32_e32 v124, v79
	v_add_f32_e32 v66, v66, v111
	v_add_f32_e32 v67, v67, v98
	v_mfma_f32_32x32x16_bf16 v[50:65], v[86:89], v[94:97], v[50:65]
	v_add_f32_e32 v66, v66, v112
	v_add_f32_e32 v67, v67, v99
	v_exp_f32_e32 v125, v80
	v_add_f32_e32 v66, v66, v113
	v_add_f32_e32 v67, v67, v100
	v_exp_f32_e32 v81, v81
	v_add_f32_e32 v66, v66, v114
	v_add_f32_e32 v67, v67, v101
	v_cvt_pk_bf16_f32 v68, v119, v120
	v_add_f32_e32 v66, v66, v115
	v_add_f32_e32 v67, v67, v102
	v_cvt_pk_bf16_f32 v69, v121, v122
	v_add_f32_e32 v66, v66, v116
	v_add_f32_e32 v67, v67, v103
	v_cvt_pk_bf16_f32 v70, v98, v99
	v_add_f32_e32 v66, v66, v106
	v_add_f32_e32 v67, v67, v104
	v_cvt_pk_bf16_f32 v71, v100, v101
	v_add_f32_e32 v66, v66, v107
	v_add_f32_e32 v67, v67, v105
	v_cvt_pk_bf16_f32 v78, v102, v103
	v_add_f32_e32 v66, v66, v108
	v_add_f32_e32 v67, v67, v123
	v_cvt_pk_bf16_f32 v79, v104, v105
	v_add_f32_e32 v66, v66, v109
	v_add_f32_e32 v67, v67, v124
	v_cvt_pk_bf16_f32 v80, v123, v124
	v_add_f32_e32 v66, v66, v117
	v_add_f32_e32 v67, v67, v125
	v_add_f32_e32 v66, v66, v118
	v_add_f32_e32 v67, v67, v81
	v_cvt_pk_bf16_f32 v81, v125, v81
	v_add_f32_e32 v66, v66, v67
	v_add_f32_e32 v66, v151, v66
	v_mov_b32_e32 v67, v66
	s_nop 1
	v_permlane32_swap_b32_e32 v66, v67
	ds_read_b64_tr_b16 v[82:83], v208 offset:0x2200
	ds_read_b64_tr_b16 v[84:85], v208 offset:0x2a00
	ds_read_b64_tr_b16 v[86:87], v208 offset:0x3200
	ds_read_b64_tr_b16 v[88:89], v208 offset:0x3a00
	s_waitcnt lgkmcnt(4)
	v_mfma_f32_32x32x16_bf16 v[2:17], v[68:71], v[74:77], v[2:17]
	s_nop 0
	v_mfma_f32_32x32x16_bf16 v[2:17], v[78:81], v[90:93], v[2:17]
	ds_read_b64_tr_b16 v[72:73], v208 offset:0x2400
	ds_read_b64_tr_b16 v[74:75], v208 offset:0x2c00
	ds_read_b64_tr_b16 v[90:91], v208 offset:0x3400
	ds_read_b64_tr_b16 v[92:93], v208 offset:0x3c00
	s_waitcnt lgkmcnt(4)
	v_mfma_f32_32x32x16_bf16 v[18:33], v[68:71], v[82:85], v[18:33]
	v_mfma_f32_32x32x16_bf16 v[18:33], v[78:81], v[86:89], v[18:33]
	ds_read_b64_tr_b16 v[82:83], v208 offset:0x2600
	ds_read_b64_tr_b16 v[84:85], v208 offset:0x2e00
	ds_read_b64_tr_b16 v[86:87], v208 offset:0x3600
	ds_read_b64_tr_b16 v[88:89], v208 offset:0x3e00
	s_waitcnt lgkmcnt(4)
	v_mfma_f32_32x32x16_bf16 v[34:49], v[68:71], v[72:75], v[34:49]
	v_mfma_f32_32x32x16_bf16 v[34:49], v[78:81], v[90:93], v[34:49]
	s_waitcnt lgkmcnt(0)
	v_mfma_f32_32x32x16_bf16 v[50:65], v[68:71], v[82:85], v[50:65]
	s_waitcnt vmcnt(0)
	s_barrier
	v_mfma_f32_32x32x16_bf16 v[50:65], v[78:81], v[86:89], v[50:65]
	s_and_saveexec_b64 s[0:1], s[2:3]
	s_cbranch_execz .LBB0_2310
	v_add_f32_e32 v66, v66, v67
	v_lshl_add_u32 v68, v165, 2, s4
	ds_write_b32 v68, v66
	s_branch .LBB0_2310
